# attention fast path without per-tile max: probability sums checked before state update, full lazy-max path as fallback and on first tile
# speedup vs baseline: 1.0063x; 1.0063x over previous
; __device__ void phase_attn(KP p, PG8_LAS unsigned char* lds, float* ldsf, int tid_in) {
;     ...
;             for (int kt = 0; kt < nt; ++kt) {
;                 if (kt + 1 < nt) AT_GLOAD(kt + 1);
;                 if (kt <= cw) {
;                     const PG8_LAS unsigned char* kb = lds + (kt & 1) * BUF;
;                     f32x4 st[4][2];
; #pragma unroll
;                     for (int f = 0; f < 4; ++f) {
;                         const bf16x8 a0 = *(const PG8_LAS bf16x8*)(kb + ka_rd + f * 16 * KS * 2);
;                         const bf16x8 a1 = *(const PG8_LAS bf16x8*)(kb + ka_rd + f * 16 * KS * 2 + 64);
;                         const bf16x8 a2 = *(const PG8_LAS bf16x8*)(kb + ka_rd + f * 16 * KS * 2 + 128);
; #pragma unroll
;                         for (int nb = 0; nb < 2; ++nb) {
;                             f32x4 c = {0.f, 0.f, 0.f, 0.f};
;                             c = __builtin_amdgcn_mfma_f32_16x16x32_bf16(a0, qf[0][nb], c, 0, 0, 0);
;                             c = __builtin_amdgcn_mfma_f32_16x16x32_bf16(a1, qf[1][nb], c, 0, 0, 0);
;                             c = __builtin_amdgcn_mfma_f32_16x16x32_bf16(a2, qf[2][nb], c, 0, 0, 0);
;                             st[f][nb] = c;
;                         }
;                     }
; #pragma unroll
;                     for (int nb = 0; nb < 2; ++nb) {
;                         float mx = -1e30f;
; #pragma unroll
;                         for (int f = 0; f < 4; ++f)
; #pragma unroll
;                             for (int r = 0; r < 4; ++r) mx = fmaxf(mx, st[f][nb][r]);
;                         mx = fmaxf(mx, shx(mx, 16, lane)); mx = fmaxf(mx, shx(mx, 32, lane));
;                         const float mn = fmaxf(mrun[nb], mx), al = __builtin_amdgcn_exp2f(mrun[nb] - mn); mrun[nb] = mn;
;                         float ps = 0.f;
; #pragma unroll
;                         for (int f = 0; f < 4; ++f)
; #pragma unroll
;                             for (int r = 0; r < 4; ++r) { const float e = __builtin_amdgcn_exp2f(st[f][nb][r] - mn); st[f][nb][r] = e; ps += e; }
;                         lrun[nb] = lrun[nb] * al + ps;
; #pragma unroll
;                         for (int df = 0; df < 4; ++df) o[df][nb] *= al;
;                     }
; #pragma unroll
;                     for (int kk = 0; kk < 2; ++kk) {
;                         bf16x8 pb[2];
; #pragma unroll
.LBB0_519:
	s_or_b64 exec, exec, s[8:9]
	global_load_dwordx4 v[50:53], v[50:51], off
	v_cmp_le_i32_e32 vcc, s12, v171
	s_and_saveexec_b64 s[8:9], vcc
	s_cbranch_execz .LBB0_521
	s_bitcmp1_b32 s12, 0
	s_cselect_b32 s12, 0x5800, 0
	s_add_i32 s12, s12, 0
	s_cmp_eq_u32 s40, 1
	s_cbranch_scc1 .Lat3_slow_1
	v_add_u32_e32 v8, s12, v167
	ds_read_b128 v[178:181], v8
	ds_read_b128 v[182:185], v8 offset:64
	ds_read_b128 v[186:189], v8 offset:128
	ds_read_b128 v[190:193], v8 offset:3328
	ds_read_b128 v[194:197], v8 offset:3392
	ds_read_b128 v[198:201], v8 offset:3456
	ds_read_b128 v[202:205], v8 offset:6656
	ds_read_b128 v[206:209], v8 offset:6720
	ds_read_b128 v[210:213], v8 offset:6784
	ds_read_b128 v[214:217], v8 offset:9984
	ds_read_b128 v[218:221], v8 offset:10048
	ds_read_b128 v[222:225], v8 offset:10112
	v_add_u32_e32 v92, s12, v170
	s_waitcnt lgkmcnt(9)
	v_mfma_f32_16x16x32_bf16 v[134:137], v[178:181], v[22:25], v[226:229]
	v_mfma_f32_16x16x32_bf16 v[134:137], v[182:185], v[26:29], v[134:137]
	v_mfma_f32_16x16x32_bf16 v[134:137], v[186:189], v[38:41], v[134:137]
	s_waitcnt lgkmcnt(6)
	v_mfma_f32_16x16x32_bf16 v[138:141], v[190:193], v[22:25], v[226:229]
	v_mfma_f32_16x16x32_bf16 v[138:141], v[194:197], v[26:29], v[138:141]
	v_mfma_f32_16x16x32_bf16 v[138:141], v[198:201], v[38:41], v[138:141]
	s_waitcnt lgkmcnt(3)
	v_mfma_f32_16x16x32_bf16 v[142:145], v[202:205], v[22:25], v[226:229]
	v_mfma_f32_16x16x32_bf16 v[142:145], v[206:209], v[26:29], v[142:145]
	v_mfma_f32_16x16x32_bf16 v[142:145], v[210:213], v[38:41], v[142:145]
	s_waitcnt lgkmcnt(0)
	v_mfma_f32_16x16x32_bf16 v[146:149], v[214:217], v[22:25], v[226:229]
	v_mfma_f32_16x16x32_bf16 v[146:149], v[218:221], v[26:29], v[146:149]
	v_mfma_f32_16x16x32_bf16 v[146:149], v[222:225], v[38:41], v[146:149]
	v_mfma_f32_16x16x32_bf16 v[76:79], v[178:181], v[42:45], v[230:233]
	v_mfma_f32_16x16x32_bf16 v[76:79], v[182:185], v[30:33], v[76:79]
	v_mfma_f32_16x16x32_bf16 v[76:79], v[186:189], v[34:37], v[76:79]
	v_exp_f32_e32 v134, v134
	v_exp_f32_e32 v135, v135
	v_mfma_f32_16x16x32_bf16 v[80:83], v[190:193], v[42:45], v[230:233]
	v_exp_f32_e32 v136, v136
	v_exp_f32_e32 v137, v137
	v_mfma_f32_16x16x32_bf16 v[80:83], v[194:197], v[30:33], v[80:83]
	v_exp_f32_e32 v138, v138
	v_exp_f32_e32 v139, v139
	v_mfma_f32_16x16x32_bf16 v[80:83], v[198:201], v[34:37], v[80:83]
	v_exp_f32_e32 v140, v140
	v_exp_f32_e32 v141, v141
	v_mfma_f32_16x16x32_bf16 v[84:87], v[202:205], v[42:45], v[230:233]
	v_exp_f32_e32 v142, v142
	v_exp_f32_e32 v143, v143
	v_mfma_f32_16x16x32_bf16 v[84:87], v[206:209], v[30:33], v[84:87]
	v_exp_f32_e32 v144, v144
	v_exp_f32_e32 v145, v145
	v_mfma_f32_16x16x32_bf16 v[84:87], v[210:213], v[34:37], v[84:87]
	v_exp_f32_e32 v146, v146
	v_exp_f32_e32 v147, v147
	v_mfma_f32_16x16x32_bf16 v[88:91], v[214:217], v[42:45], v[230:233]
	v_exp_f32_e32 v148, v148
	v_exp_f32_e32 v149, v149
	v_mfma_f32_16x16x32_bf16 v[88:91], v[218:221], v[30:33], v[88:91]
	v_mfma_f32_16x16x32_bf16 v[88:91], v[222:225], v[34:37], v[88:91]
	ds_read_b64 v[178:179], v92 offset:13312
	ds_read_b64 v[180:181], v92 offset:13344
	ds_read_b64 v[182:183], v92 offset:15616
	ds_read_b64 v[184:185], v92 offset:15648
	ds_read_b64 v[186:187], v92 offset:17920
	ds_read_b64 v[188:189], v92 offset:17952
	ds_read_b64 v[190:191], v92 offset:20224
	ds_read_b64 v[192:193], v92 offset:20256
	ds_read_b64 v[194:195], v92 offset:13376
	ds_read_b64 v[196:197], v92 offset:13408
	ds_read_b64 v[198:199], v92 offset:15680
	ds_read_b64 v[200:201], v92 offset:15712
	ds_read_b64 v[202:203], v92 offset:17984
	ds_read_b64 v[204:205], v92 offset:18016
	ds_read_b64 v[206:207], v92 offset:20288
	ds_read_b64 v[208:209], v92 offset:20320
	v_exp_f32_e32 v76, v76
	v_exp_f32_e32 v77, v77
	v_exp_f32_e32 v78, v78
	v_exp_f32_e32 v79, v79
	v_exp_f32_e32 v80, v80
	v_exp_f32_e32 v81, v81
	v_exp_f32_e32 v82, v82
	v_exp_f32_e32 v83, v83
	v_exp_f32_e32 v84, v84
	v_exp_f32_e32 v85, v85
	v_exp_f32_e32 v86, v86
	v_exp_f32_e32 v87, v87
	v_exp_f32_e32 v88, v88
	v_exp_f32_e32 v89, v89
	v_exp_f32_e32 v90, v90
	v_exp_f32_e32 v91, v91
	v_pk_add_f32 v[162:163], v[134:135], v[136:137]
	v_pk_add_f32 v[174:175], v[138:139], v[140:141]
	v_pk_add_f32 v[162:163], v[162:163], v[142:143]
	v_pk_add_f32 v[174:175], v[174:175], v[144:145]
	v_pk_add_f32 v[162:163], v[162:163], v[146:147]
	v_pk_add_f32 v[174:175], v[174:175], v[148:149]
	v_pk_add_f32 v[162:163], v[162:163], v[174:175]
	v_add_f32_e32 v154, v162, v163
	v_pk_add_f32 v[176:177], v[76:77], v[78:79]
	v_pk_add_f32 v[70:71], v[80:81], v[82:83]
	v_pk_add_f32 v[176:177], v[176:177], v[84:85]
	v_pk_add_f32 v[70:71], v[70:71], v[86:87]
	v_pk_add_f32 v[176:177], v[176:177], v[88:89]
	v_pk_add_f32 v[70:71], v[70:71], v[90:91]
	v_pk_add_f32 v[176:177], v[176:177], v[70:71]
	v_add_f32_e32 v155, v176, v177
	v_max_f32_e32 v156, v154, v155
	v_cmp_ngt_f32_e32 vcc, 0x45800000, v156
	v_cvt_pk_bf16_f32 v134, v134, v135
	v_cvt_pk_bf16_f32 v135, v136, v137
	v_cvt_pk_bf16_f32 v136, v138, v139
	v_cvt_pk_bf16_f32 v137, v140, v141
	s_and_b64 vcc, exec, vcc
	s_cbranch_vccnz .Lat3_slowq_1
	v_add_f32_e32 v125, v125, v154
	v_add_f32_e32 v124, v124, v155
	v_cvt_pk_bf16_f32 v142, v142, v143
	v_cvt_pk_bf16_f32 v143, v144, v145
	v_cvt_pk_bf16_f32 v144, v146, v147
	v_cvt_pk_bf16_f32 v145, v148, v149
	s_waitcnt lgkmcnt(8)
	v_mfma_f32_16x16x32_bf16 v[54:57], v[178:181], v[134:137], v[54:57]
	v_cvt_pk_bf16_f32 v76, v76, v77
	v_mfma_f32_16x16x32_bf16 v[58:61], v[182:185], v[134:137], v[58:61]
	v_cvt_pk_bf16_f32 v77, v78, v79
	v_mfma_f32_16x16x32_bf16 v[62:65], v[186:189], v[134:137], v[62:65]
	v_cvt_pk_bf16_f32 v78, v80, v81
	v_mfma_f32_16x16x32_bf16 v[66:69], v[190:193], v[134:137], v[66:69]
	v_cvt_pk_bf16_f32 v79, v82, v83
	s_waitcnt lgkmcnt(0)
	v_mfma_f32_16x16x32_bf16 v[54:57], v[194:197], v[142:145], v[54:57]
	v_cvt_pk_bf16_f32 v84, v84, v85
	v_mfma_f32_16x16x32_bf16 v[58:61], v[198:201], v[142:145], v[58:61]
	v_cvt_pk_bf16_f32 v85, v86, v87
	v_mfma_f32_16x16x32_bf16 v[62:65], v[202:205], v[142:145], v[62:65]
	v_cvt_pk_bf16_f32 v86, v88, v89
	v_mfma_f32_16x16x32_bf16 v[66:69], v[206:209], v[142:145], v[66:69]
	v_cvt_pk_bf16_f32 v87, v90, v91
	v_mfma_f32_16x16x32_bf16 v[4:7], v[178:181], v[76:79], v[4:7]
	v_mfma_f32_16x16x32_bf16 v[10:13], v[182:185], v[76:79], v[10:13]
	v_mfma_f32_16x16x32_bf16 v[14:17], v[186:189], v[76:79], v[14:17]
	v_mfma_f32_16x16x32_bf16 v[18:21], v[190:193], v[76:79], v[18:21]
	v_mfma_f32_16x16x32_bf16 v[4:7], v[194:197], v[84:87], v[4:7]
	v_mfma_f32_16x16x32_bf16 v[10:13], v[198:201], v[84:87], v[10:13]
	v_mfma_f32_16x16x32_bf16 v[14:17], v[202:205], v[84:87], v[14:17]
	v_mfma_f32_16x16x32_bf16 v[18:21], v[206:209], v[84:87], v[18:21]
	s_branch .Lat3_end_1

; #define PG8_LAS __attribute__((address_space(3)))
; __device__ __forceinline__ float shx(float v, int o, int lane) { return __int_as_float(__builtin_amdgcn_ds_bpermute((lane ^ o) << 2, __float_as_int(v))); }
; __device__ void phase_attn(KP p, PG8_LAS unsigned char* lds, float* ldsf, int tid_in) {
;     ...
;                     for (int f = 0; f < 4; ++f) {
;                         const bf16x8 a0 = *(const PG8_LAS bf16x8*)(kb + ka_rd + f * 16 * KS * 2);
;                         const bf16x8 a1 = *(const PG8_LAS bf16x8*)(kb + ka_rd + f * 16 * KS * 2 + 64);
;                         const bf16x8 a2 = *(const PG8_LAS bf16x8*)(kb + ka_rd + f * 16 * KS * 2 + 128);
; #pragma unroll
;                         for (int nb = 0; nb < 2; ++nb) {
;                             f32x4 c = {0.f, 0.f, 0.f, 0.f};
;                             c = __builtin_amdgcn_mfma_f32_16x16x32_bf16(a0, qf[0][nb], c, 0, 0, 0);
;                             c = __builtin_amdgcn_mfma_f32_16x16x32_bf16(a1, qf[1][nb], c, 0, 0, 0);
;                             c = __builtin_amdgcn_mfma_f32_16x16x32_bf16(a2, qf[2][nb], c, 0, 0, 0);
;                             st[f][nb] = c;
;                         }
;                     }
; #pragma unroll
;                     for (int nb = 0; nb < 2; ++nb) {
;                         float mx = -1e30f;
; #pragma unroll
;                         for (int f = 0; f < 4; ++f)
; #pragma unroll
;                             for (int r = 0; r < 4; ++r) mx = fmaxf(mx, st[f][nb][r]);
;                         mx = fmaxf(mx, shx(mx, 16, lane)); mx = fmaxf(mx, shx(mx, 32, lane));
;                         const float mn = fmaxf(mrun[nb], mx), al = __builtin_amdgcn_exp2f(mrun[nb] - mn); mrun[nb] = mn;
.Lat3_slow_1:
	v_add_u32_e32 v8, s12, v167
	ds_read_b128 v[178:181], v8
	ds_read_b128 v[182:185], v8 offset:64
	ds_read_b128 v[186:189], v8 offset:128
	ds_read_b128 v[190:193], v8 offset:3328
	ds_read_b128 v[194:197], v8 offset:3392
	ds_read_b128 v[198:201], v8 offset:3456
	ds_read_b128 v[202:205], v8 offset:6656
	ds_read_b128 v[206:209], v8 offset:6720
	ds_read_b128 v[210:213], v8 offset:6784
	ds_read_b128 v[214:217], v8 offset:9984
	ds_read_b128 v[218:221], v8 offset:10048
	ds_read_b128 v[222:225], v8 offset:10112
	v_add_u32_e32 v92, s12, v170
	s_cmp_eq_u32 s40, 1
	s_cselect_b64 s[14:15], -1, 0
	s_waitcnt lgkmcnt(9)
	v_mfma_f32_16x16x32_bf16 v[134:137], v[178:181], v[22:25], v[226:229]
	v_mfma_f32_16x16x32_bf16 v[134:137], v[182:185], v[26:29], v[134:137]
	v_mfma_f32_16x16x32_bf16 v[134:137], v[186:189], v[38:41], v[134:137]
	s_waitcnt lgkmcnt(6)
	v_mfma_f32_16x16x32_bf16 v[138:141], v[190:193], v[22:25], v[226:229]
	v_mfma_f32_16x16x32_bf16 v[138:141], v[194:197], v[26:29], v[138:141]
	v_mfma_f32_16x16x32_bf16 v[138:141], v[198:201], v[38:41], v[138:141]
	s_waitcnt lgkmcnt(3)
	v_mfma_f32_16x16x32_bf16 v[142:145], v[202:205], v[22:25], v[226:229]
	v_mfma_f32_16x16x32_bf16 v[142:145], v[206:209], v[26:29], v[142:145]
	v_mfma_f32_16x16x32_bf16 v[142:145], v[210:213], v[38:41], v[142:145]
	s_waitcnt lgkmcnt(0)
	v_mfma_f32_16x16x32_bf16 v[146:149], v[214:217], v[22:25], v[226:229]
	v_mfma_f32_16x16x32_bf16 v[146:149], v[218:221], v[26:29], v[146:149]
	v_mfma_f32_16x16x32_bf16 v[146:149], v[222:225], v[38:41], v[146:149]
	v_mfma_f32_16x16x32_bf16 v[76:79], v[178:181], v[42:45], v[230:233]
	v_max3_f32 v156, v134, v135, v136
	v_max3_f32 v156, v156, v137, v138
	v_mfma_f32_16x16x32_bf16 v[76:79], v[182:185], v[30:33], v[76:79]
	v_max3_f32 v156, v156, v139, v140
	v_max3_f32 v156, v156, v141, v142
	v_mfma_f32_16x16x32_bf16 v[76:79], v[186:189], v[34:37], v[76:79]
	v_max3_f32 v156, v156, v143, v144
	v_max3_f32 v156, v156, v145, v146
	v_mfma_f32_16x16x32_bf16 v[80:83], v[190:193], v[42:45], v[230:233]
	v_max3_f32 v156, v156, v147, v148
	v_max_f32_e32 v156, v156, v149
	v_cmp_lt_f32_e32 vcc, 0x41000000, v156
	v_mfma_f32_16x16x32_bf16 v[80:83], v[194:197], v[30:33], v[80:83]
	v_mfma_f32_16x16x32_bf16 v[80:83], v[198:201], v[34:37], v[80:83]
	s_or_b64 vcc, vcc, s[14:15]
	s_cbranch_vccnz .Lat_resc0_1

; __device__ void phase_attn(KP p, PG8_LAS unsigned char* lds, float* ldsf, int tid_in) {
;     ...
;             for (int kt = 0; kt < nt; ++kt) {
;                 if (kt + 1 < nt) AT_GLOAD(kt + 1);
;                 if (kt <= cw) {
;                     const PG8_LAS unsigned char* kb = lds + (kt & 1) * BUF;
;                     f32x4 st[4][2];
; #pragma unroll
;                     for (int f = 0; f < 4; ++f) {
;                         const bf16x8 a0 = *(const PG8_LAS bf16x8*)(kb + ka_rd + f * 16 * KS * 2);
;                         const bf16x8 a1 = *(const PG8_LAS bf16x8*)(kb + ka_rd + f * 16 * KS * 2 + 64);
;                         const bf16x8 a2 = *(const PG8_LAS bf16x8*)(kb + ka_rd + f * 16 * KS * 2 + 128);
; #pragma unroll
;                         for (int nb = 0; nb < 2; ++nb) {
;                             f32x4 c = {0.f, 0.f, 0.f, 0.f};
;                             c = __builtin_amdgcn_mfma_f32_16x16x32_bf16(a0, qf[0][nb], c, 0, 0, 0);
;                             c = __builtin_amdgcn_mfma_f32_16x16x32_bf16(a1, qf[1][nb], c, 0, 0, 0);
;                             c = __builtin_amdgcn_mfma_f32_16x16x32_bf16(a2, qf[2][nb], c, 0, 0, 0);
;                             st[f][nb] = c;
;                         }
;                     }
; #pragma unroll
;                     for (int nb = 0; nb < 2; ++nb) {
;                         float mx = -1e30f;
; #pragma unroll
;                         for (int f = 0; f < 4; ++f)
; #pragma unroll
;                             for (int r = 0; r < 4; ++r) mx = fmaxf(mx, st[f][nb][r]);
;                         mx = fmaxf(mx, shx(mx, 16, lane)); mx = fmaxf(mx, shx(mx, 32, lane));
;                         const float mn = fmaxf(mrun[nb], mx), al = __builtin_amdgcn_exp2f(mrun[nb] - mn); mrun[nb] = mn;
;                         float ps = 0.f;
; #pragma unroll
;                         for (int f = 0; f < 4; ++f)
; #pragma unroll
;                             for (int r = 0; r < 4; ++r) { const float e = __builtin_amdgcn_exp2f(st[f][nb][r] - mn); st[f][nb][r] = e; ps += e; }
;                         lrun[nb] = lrun[nb] * al + ps;
; #pragma unroll
;                         for (int df = 0; df < 4; ++df) o[df][nb] *= al;
;                     }
; #pragma unroll
;                     for (int kk = 0; kk < 2; ++kk) {
;                         bf16x8 pb[2];
; #pragma unroll
.LBB0_525:
	s_add_i32 s8, s0, -2
	v_cmp_lt_i32_e32 vcc, s8, v171
	s_and_saveexec_b64 s[8:9], vcc
	s_cbranch_execz .LBB0_511
	v_add_u32_e32 v8, s12, v167
	ds_read_b128 v[178:181], v8
	ds_read_b128 v[182:185], v8 offset:64
	ds_read_b128 v[186:189], v8 offset:128
	ds_read_b128 v[190:193], v8 offset:3328
	ds_read_b128 v[194:197], v8 offset:3392
	ds_read_b128 v[198:201], v8 offset:3456
	ds_read_b128 v[202:205], v8 offset:6656
	ds_read_b128 v[206:209], v8 offset:6720
	ds_read_b128 v[210:213], v8 offset:6784
	ds_read_b128 v[214:217], v8 offset:9984
	ds_read_b128 v[218:221], v8 offset:10048
	ds_read_b128 v[222:225], v8 offset:10112
	v_add_u32_e32 v92, s12, v170
	s_waitcnt lgkmcnt(9)
	v_mfma_f32_16x16x32_bf16 v[134:137], v[178:181], v[22:25], v[226:229]
	v_mfma_f32_16x16x32_bf16 v[134:137], v[182:185], v[26:29], v[134:137]
	v_mfma_f32_16x16x32_bf16 v[134:137], v[186:189], v[38:41], v[134:137]
	s_waitcnt lgkmcnt(6)
	v_mfma_f32_16x16x32_bf16 v[138:141], v[190:193], v[22:25], v[226:229]
	v_mfma_f32_16x16x32_bf16 v[138:141], v[194:197], v[26:29], v[138:141]
	v_mfma_f32_16x16x32_bf16 v[138:141], v[198:201], v[38:41], v[138:141]
	s_waitcnt lgkmcnt(3)
	v_mfma_f32_16x16x32_bf16 v[142:145], v[202:205], v[22:25], v[226:229]
	v_mfma_f32_16x16x32_bf16 v[142:145], v[206:209], v[26:29], v[142:145]
	v_mfma_f32_16x16x32_bf16 v[142:145], v[210:213], v[38:41], v[142:145]
	s_waitcnt lgkmcnt(0)
	v_mfma_f32_16x16x32_bf16 v[146:149], v[214:217], v[22:25], v[226:229]
	v_mfma_f32_16x16x32_bf16 v[146:149], v[218:221], v[26:29], v[146:149]
	v_mfma_f32_16x16x32_bf16 v[146:149], v[222:225], v[38:41], v[146:149]
	v_mfma_f32_16x16x32_bf16 v[76:79], v[178:181], v[42:45], v[230:233]
	v_mfma_f32_16x16x32_bf16 v[76:79], v[182:185], v[30:33], v[76:79]
	v_mfma_f32_16x16x32_bf16 v[76:79], v[186:189], v[34:37], v[76:79]
	v_exp_f32_e32 v134, v134
	v_exp_f32_e32 v135, v135
	v_mfma_f32_16x16x32_bf16 v[80:83], v[190:193], v[42:45], v[230:233]
	v_exp_f32_e32 v136, v136
	v_exp_f32_e32 v137, v137
	v_mfma_f32_16x16x32_bf16 v[80:83], v[194:197], v[30:33], v[80:83]
	v_exp_f32_e32 v138, v138
	v_exp_f32_e32 v139, v139
	v_mfma_f32_16x16x32_bf16 v[80:83], v[198:201], v[34:37], v[80:83]
	v_exp_f32_e32 v140, v140
	v_exp_f32_e32 v141, v141
	v_mfma_f32_16x16x32_bf16 v[84:87], v[202:205], v[42:45], v[230:233]
	v_exp_f32_e32 v142, v142
	v_exp_f32_e32 v143, v143
	v_mfma_f32_16x16x32_bf16 v[84:87], v[206:209], v[30:33], v[84:87]
	v_exp_f32_e32 v144, v144
	v_exp_f32_e32 v145, v145
	v_mfma_f32_16x16x32_bf16 v[84:87], v[210:213], v[34:37], v[84:87]
	v_exp_f32_e32 v146, v146
	v_exp_f32_e32 v147, v147
	v_mfma_f32_16x16x32_bf16 v[88:91], v[214:217], v[42:45], v[230:233]
	v_exp_f32_e32 v148, v148
	v_exp_f32_e32 v149, v149
	v_mfma_f32_16x16x32_bf16 v[88:91], v[218:221], v[30:33], v[88:91]
	v_mfma_f32_16x16x32_bf16 v[88:91], v[222:225], v[34:37], v[88:91]
	ds_read_b64 v[178:179], v92 offset:13312
	ds_read_b64 v[180:181], v92 offset:13344
	ds_read_b64 v[182:183], v92 offset:15616
	ds_read_b64 v[184:185], v92 offset:15648
	ds_read_b64 v[186:187], v92 offset:17920
	ds_read_b64 v[188:189], v92 offset:17952
	ds_read_b64 v[190:191], v92 offset:20224
	ds_read_b64 v[192:193], v92 offset:20256
	ds_read_b64 v[194:195], v92 offset:13376
	ds_read_b64 v[196:197], v92 offset:13408
	ds_read_b64 v[198:199], v92 offset:15680
	ds_read_b64 v[200:201], v92 offset:15712
	ds_read_b64 v[202:203], v92 offset:17984
	ds_read_b64 v[204:205], v92 offset:18016
	ds_read_b64 v[206:207], v92 offset:20288
	ds_read_b64 v[208:209], v92 offset:20320
	v_exp_f32_e32 v76, v76
	v_exp_f32_e32 v77, v77
	v_exp_f32_e32 v78, v78
	v_exp_f32_e32 v79, v79
	v_exp_f32_e32 v80, v80
	v_exp_f32_e32 v81, v81
	v_exp_f32_e32 v82, v82
	v_exp_f32_e32 v83, v83
	v_exp_f32_e32 v84, v84
	v_exp_f32_e32 v85, v85
	v_exp_f32_e32 v86, v86
	v_exp_f32_e32 v87, v87
	v_exp_f32_e32 v88, v88
	v_exp_f32_e32 v89, v89
	v_exp_f32_e32 v90, v90
	v_exp_f32_e32 v91, v91
	v_pk_add_f32 v[162:163], v[134:135], v[136:137]
	v_pk_add_f32 v[174:175], v[138:139], v[140:141]
	v_pk_add_f32 v[162:163], v[162:163], v[142:143]
	v_pk_add_f32 v[174:175], v[174:175], v[144:145]
	v_pk_add_f32 v[162:163], v[162:163], v[146:147]
	v_pk_add_f32 v[174:175], v[174:175], v[148:149]
	v_pk_add_f32 v[162:163], v[162:163], v[174:175]
	v_add_f32_e32 v154, v162, v163
	v_pk_add_f32 v[176:177], v[76:77], v[78:79]
	v_pk_add_f32 v[70:71], v[80:81], v[82:83]
	v_pk_add_f32 v[176:177], v[176:177], v[84:85]
	v_pk_add_f32 v[70:71], v[70:71], v[86:87]
	v_pk_add_f32 v[176:177], v[176:177], v[88:89]
	v_pk_add_f32 v[70:71], v[70:71], v[90:91]
	v_pk_add_f32 v[176:177], v[176:177], v[70:71]
	v_add_f32_e32 v155, v176, v177
	v_max_f32_e32 v156, v154, v155
	v_cmp_ngt_f32_e32 vcc, 0x45800000, v156
	v_cvt_pk_bf16_f32 v134, v134, v135
	v_cvt_pk_bf16_f32 v135, v136, v137
	v_cvt_pk_bf16_f32 v136, v138, v139
	v_cvt_pk_bf16_f32 v137, v140, v141
	s_and_b64 vcc, exec, vcc
	s_cbranch_vccnz .Lat3_slowq_2
	v_add_f32_e32 v125, v125, v154
	v_add_f32_e32 v124, v124, v155
	v_cvt_pk_bf16_f32 v142, v142, v143
	v_cvt_pk_bf16_f32 v143, v144, v145
	v_cvt_pk_bf16_f32 v144, v146, v147
	v_cvt_pk_bf16_f32 v145, v148, v149
	s_waitcnt lgkmcnt(8)
	v_mfma_f32_16x16x32_bf16 v[54:57], v[178:181], v[134:137], v[54:57]
	v_cvt_pk_bf16_f32 v76, v76, v77
	v_mfma_f32_16x16x32_bf16 v[58:61], v[182:185], v[134:137], v[58:61]
	v_cvt_pk_bf16_f32 v77, v78, v79
	v_mfma_f32_16x16x32_bf16 v[62:65], v[186:189], v[134:137], v[62:65]
	v_cvt_pk_bf16_f32 v78, v80, v81
	v_mfma_f32_16x16x32_bf16 v[66:69], v[190:193], v[134:137], v[66:69]
	v_cvt_pk_bf16_f32 v79, v82, v83
	s_waitcnt lgkmcnt(0)
	v_mfma_f32_16x16x32_bf16 v[54:57], v[194:197], v[142:145], v[54:57]
	v_cvt_pk_bf16_f32 v84, v84, v85
	v_mfma_f32_16x16x32_bf16 v[58:61], v[198:201], v[142:145], v[58:61]
	v_cvt_pk_bf16_f32 v85, v86, v87
	v_mfma_f32_16x16x32_bf16 v[62:65], v[202:205], v[142:145], v[62:65]
	v_cvt_pk_bf16_f32 v86, v88, v89
	v_mfma_f32_16x16x32_bf16 v[66:69], v[206:209], v[142:145], v[66:69]
	v_cvt_pk_bf16_f32 v87, v90, v91
	v_mfma_f32_16x16x32_bf16 v[4:7], v[178:181], v[76:79], v[4:7]
	v_mfma_f32_16x16x32_bf16 v[10:13], v[182:185], v[76:79], v[10:13]
	v_mfma_f32_16x16x32_bf16 v[14:17], v[186:189], v[76:79], v[14:17]
	v_mfma_f32_16x16x32_bf16 v[18:21], v[190:193], v[76:79], v[18:21]
	v_mfma_f32_16x16x32_bf16 v[4:7], v[194:197], v[84:87], v[4:7]
	v_mfma_f32_16x16x32_bf16 v[10:13], v[198:201], v[84:87], v[10:13]
	v_mfma_f32_16x16x32_bf16 v[14:17], v[202:205], v[84:87], v[14:17]
	v_mfma_f32_16x16x32_bf16 v[18:21], v[206:209], v[84:87], v[18:21]
	s_branch .Lat3_end_2

; #define PG8_LAS __attribute__((address_space(3)))
; __device__ __forceinline__ float shx(float v, int o, int lane) { return __int_as_float(__builtin_amdgcn_ds_bpermute((lane ^ o) << 2, __float_as_int(v))); }
; __device__ void phase_attn(KP p, PG8_LAS unsigned char* lds, float* ldsf, int tid_in) {
;     ...
;                     for (int f = 0; f < 4; ++f) {
;                         const bf16x8 a0 = *(const PG8_LAS bf16x8*)(kb + ka_rd + f * 16 * KS * 2);
;                         const bf16x8 a1 = *(const PG8_LAS bf16x8*)(kb + ka_rd + f * 16 * KS * 2 + 64);
;                         const bf16x8 a2 = *(const PG8_LAS bf16x8*)(kb + ka_rd + f * 16 * KS * 2 + 128);
; #pragma unroll
;                         for (int nb = 0; nb < 2; ++nb) {
;                             f32x4 c = {0.f, 0.f, 0.f, 0.f};
;                             c = __builtin_amdgcn_mfma_f32_16x16x32_bf16(a0, qf[0][nb], c, 0, 0, 0);
;                             c = __builtin_amdgcn_mfma_f32_16x16x32_bf16(a1, qf[1][nb], c, 0, 0, 0);
;                             c = __builtin_amdgcn_mfma_f32_16x16x32_bf16(a2, qf[2][nb], c, 0, 0, 0);
;                             st[f][nb] = c;
;                         }
;                     }
; #pragma unroll
;                     for (int nb = 0; nb < 2; ++nb) {
;                         float mx = -1e30f;
; #pragma unroll
;                         for (int f = 0; f < 4; ++f)
; #pragma unroll
;                             for (int r = 0; r < 4; ++r) mx = fmaxf(mx, st[f][nb][r]);
;                         mx = fmaxf(mx, shx(mx, 16, lane)); mx = fmaxf(mx, shx(mx, 32, lane));
;                         const float mn = fmaxf(mrun[nb], mx), al = __builtin_amdgcn_exp2f(mrun[nb] - mn); mrun[nb] = mn;
.Lat3_slow_2:
	v_add_u32_e32 v8, s12, v167
	ds_read_b128 v[178:181], v8
	ds_read_b128 v[182:185], v8 offset:64
	ds_read_b128 v[186:189], v8 offset:128
	ds_read_b128 v[190:193], v8 offset:3328
	ds_read_b128 v[194:197], v8 offset:3392
	ds_read_b128 v[198:201], v8 offset:3456
	ds_read_b128 v[202:205], v8 offset:6656
	ds_read_b128 v[206:209], v8 offset:6720
	ds_read_b128 v[210:213], v8 offset:6784
	ds_read_b128 v[214:217], v8 offset:9984
	ds_read_b128 v[218:221], v8 offset:10048
	ds_read_b128 v[222:225], v8 offset:10112
	v_add_u32_e32 v92, s12, v170
	s_mov_b64 s[14:15], 0
	s_waitcnt lgkmcnt(9)
	v_mfma_f32_16x16x32_bf16 v[134:137], v[178:181], v[22:25], v[226:229]
	v_mfma_f32_16x16x32_bf16 v[134:137], v[182:185], v[26:29], v[134:137]
	v_mfma_f32_16x16x32_bf16 v[134:137], v[186:189], v[38:41], v[134:137]
	s_waitcnt lgkmcnt(6)
	v_mfma_f32_16x16x32_bf16 v[138:141], v[190:193], v[22:25], v[226:229]
	v_mfma_f32_16x16x32_bf16 v[138:141], v[194:197], v[26:29], v[138:141]
	v_mfma_f32_16x16x32_bf16 v[138:141], v[198:201], v[38:41], v[138:141]
	s_waitcnt lgkmcnt(3)
	v_mfma_f32_16x16x32_bf16 v[142:145], v[202:205], v[22:25], v[226:229]
	v_mfma_f32_16x16x32_bf16 v[142:145], v[206:209], v[26:29], v[142:145]
	v_mfma_f32_16x16x32_bf16 v[142:145], v[210:213], v[38:41], v[142:145]
	s_waitcnt lgkmcnt(0)
	v_mfma_f32_16x16x32_bf16 v[146:149], v[214:217], v[22:25], v[226:229]
	v_mfma_f32_16x16x32_bf16 v[146:149], v[218:221], v[26:29], v[146:149]
	v_mfma_f32_16x16x32_bf16 v[146:149], v[222:225], v[38:41], v[146:149]
	v_mfma_f32_16x16x32_bf16 v[76:79], v[178:181], v[42:45], v[230:233]
	v_max3_f32 v156, v134, v135, v136
	v_max3_f32 v156, v156, v137, v138
	v_mfma_f32_16x16x32_bf16 v[76:79], v[182:185], v[30:33], v[76:79]
	v_max3_f32 v156, v156, v139, v140
	v_max3_f32 v156, v156, v141, v142
	v_mfma_f32_16x16x32_bf16 v[76:79], v[186:189], v[34:37], v[76:79]
	v_max3_f32 v156, v156, v143, v144
	v_max3_f32 v156, v156, v145, v146
	v_mfma_f32_16x16x32_bf16 v[80:83], v[190:193], v[42:45], v[230:233]
	v_max3_f32 v156, v156, v147, v148
	v_max_f32_e32 v156, v156, v149
	v_cmp_lt_f32_e32 vcc, 0x41000000, v156
	v_mfma_f32_16x16x32_bf16 v[80:83], v[194:197], v[30:33], v[80:83]
	v_mfma_f32_16x16x32_bf16 v[80:83], v[198:201], v[34:37], v[80:83]
	s_or_b64 vcc, vcc, s[14:15]
	s_cbranch_vccnz .Lat_resc0_2

; #define AT_LSTORE(bf_) do { PG8_LAS unsigned char* bb_ = lds + (bf_) * BUF; *(PG8_LAS u32x4v*)(bb_ + k_st) = r0; \
;                 if (lo) { *(PG8_LAS u32x4v*)(bb_ + r_st) = r1; *(PG8_LAS u32x4v*)(bb_ + v_st) = r2; } else { *(PG8_LAS u32x4v*)(bb_ + v_st) = r1; } } while (0)
; __device__ void phase_attn(KP p, PG8_LAS unsigned char* lds, float* ldsf, int tid_in) {
;     ...
;                 }
;                 if (kt + 1 < nt) AT_LSTORE((kt + 1) & 1);
;                 __syncthreads();
;             }
.Lat3_end_2:
	s_branch .LBB0_511
